# FoX flash loop: output accumulators stay in place across both unrolled tile steps (removed 32 v_mov_b64 copies and two MFMA drains per two tiles)
# baseline (speedup 1.0000x reference)
.LBB0_798:
	v_exp_f32_e32 v2, v68
	v_exp_f32_e32 v3, v69
	v_exp_f32_e32 v52, v52
	v_exp_f32_e32 v53, v53
	v_exp_f32_e32 v70, v70
	v_exp_f32_e32 v71, v71
	v_exp_f32_e32 v54, v54
	v_exp_f32_e32 v55, v55
	v_pk_add_f32 v[68:69], v[2:3], 0 op_sel_hi:[1,0]
	v_exp_f32_e32 v72, v72
	v_exp_f32_e32 v73, v73
	v_pk_add_f32 v[68:69], v[52:53], v[68:69]
	v_exp_f32_e32 v56, v56
	v_exp_f32_e32 v57, v57
	v_pk_add_f32 v[68:69], v[70:71], v[68:69]
	v_exp_f32_e32 v74, v74
	v_exp_f32_e32 v75, v75
	v_pk_add_f32 v[68:69], v[54:55], v[68:69]
	v_exp_f32_e32 v58, v58
	v_exp_f32_e32 v59, v59
	v_pk_add_f32 v[68:69], v[72:73], v[68:69]
	v_exp_f32_e32 v76, v76
	v_exp_f32_e32 v77, v77
	v_pk_add_f32 v[68:69], v[56:57], v[68:69]
	v_exp_f32_e32 v60, v60
	v_exp_f32_e32 v61, v61
	v_pk_add_f32 v[68:69], v[74:75], v[68:69]
	v_exp_f32_e32 v78, v78
	v_exp_f32_e32 v79, v79
	v_pk_add_f32 v[68:69], v[58:59], v[68:69]
	v_exp_f32_e32 v62, v62
	v_exp_f32_e32 v63, v63
	v_pk_add_f32 v[68:69], v[76:77], v[68:69]
	v_exp_f32_e32 v80, v80
	v_exp_f32_e32 v81, v81
	v_pk_add_f32 v[68:69], v[60:61], v[68:69]
	v_exp_f32_e32 v64, v64
	v_exp_f32_e32 v65, v65
	v_pk_add_f32 v[68:69], v[78:79], v[68:69]
	v_exp_f32_e32 v82, v82
	v_exp_f32_e32 v83, v83
	v_pk_add_f32 v[68:69], v[62:63], v[68:69]
	v_exp_f32_e32 v66, v66
	v_exp_f32_e32 v67, v67
	v_pk_add_f32 v[68:69], v[80:81], v[68:69]
	v_cvt_pk_bf16_f32 v88, v60, v61
	v_pk_add_f32 v[68:69], v[64:65], v[68:69]
	v_cvt_pk_bf16_f32 v89, v62, v63
	v_pk_add_f32 v[68:69], v[82:83], v[68:69]
	s_add_i32 s8, s17, 1
	v_pk_add_f32 v[68:69], v[66:67], v[68:69]
	s_cmp_lg_u32 s8, 3
	v_pk_add_f32 v[84:85], v[68:69], v[68:69] op_sel:[0,1] op_sel_hi:[1,0]
	v_cvt_pk_bf16_f32 v69, v70, v71
	v_cvt_pk_bf16_f32 v70, v72, v73
	v_cvt_pk_bf16_f32 v71, v74, v75
	v_cvt_pk_bf16_f32 v72, v76, v77
	v_cvt_pk_bf16_f32 v73, v78, v79
	v_cvt_pk_bf16_f32 v74, v80, v81
	v_cvt_pk_bf16_f32 v75, v82, v83
	v_cvt_pk_bf16_f32 v76, v52, v53
	v_cvt_pk_bf16_f32 v77, v54, v55
	v_cvt_pk_bf16_f32 v78, v56, v57
	v_cvt_pk_bf16_f32 v79, v58, v59
	ds_read_b128 v[52:55], v0 offset:9216
	ds_read_b128 v[56:59], v0 offset:9248
	ds_read_b128 v[60:63], v0 offset:9280
	ds_read_b128 v[80:83], v0 offset:9312
	s_cselect_b32 s22, s8, 0
	s_add_i32 s8, s22, 1
	s_cmp_lg_u32 s8, 3
	v_mov_b32_e32 v85, v84
	s_cselect_b32 s17, s8, 0
	s_nop 0
	v_permlane32_swap_b32_e32 v84, v85
	v_cvt_pk_bf16_f32 v68, v2, v3
	v_cvt_pk_bf16_f32 v90, v64, v65
	v_cvt_pk_bf16_f32 v91, v66, v67
	s_waitcnt lgkmcnt(3)
	v_mfma_f32_32x32x16_bf16 v[36:51], v[52:55], v[68:71], v[36:51]
	s_waitcnt lgkmcnt(2)
	v_mfma_f32_32x32x16_bf16 v[36:51], v[56:59], v[72:75], v[36:51]
	s_waitcnt lgkmcnt(1)
	v_mfma_f32_32x32x16_bf16 v[36:51], v[60:63], v[76:79], v[36:51]
	s_waitcnt lgkmcnt(0)
	v_mfma_f32_32x32x16_bf16 v[36:51], v[80:83], v[88:91], v[36:51]
	ds_read_b128 v[52:55], v0 offset:13824
	ds_read_b128 v[56:59], v0 offset:13856
	ds_read_b128 v[60:63], v0 offset:13888
	ds_read_b128 v[64:67], v0 offset:13920
	s_waitcnt lgkmcnt(3)
	v_mfma_f32_32x32x16_bf16 v[20:35], v[52:55], v[68:71], v[20:35]
	s_waitcnt lgkmcnt(2)
	v_mfma_f32_32x32x16_bf16 v[20:35], v[56:59], v[72:75], v[20:35]
	s_waitcnt lgkmcnt(1)
	v_mfma_f32_32x32x16_bf16 v[20:35], v[60:63], v[76:79], v[20:35]
	s_waitcnt lgkmcnt(0)
	v_mfma_f32_32x32x16_bf16 v[20:35], v[64:67], v[88:91], v[20:35]
	s_add_i32 s21, s13, -2
	s_cmp_ge_i32 s21, s12
	s_cbranch_scc1 .LBB0_802
	s_mul_i32 s8, s17, 0x4900
	s_add_i32 s10, s33, s8
	v_add3_u32 v0, s10, v171, v166
	s_waitcnt vmcnt(1)
	ds_write_b128 v0, v[132:135]
	s_waitcnt vmcnt(0)
	ds_write_b128 v0, v[136:139] offset:9216
	s_and_saveexec_b64 s[8:9], s[6:7]
	s_cbranch_execz .LBB0_801
	v_add_f32_e32 v170, v170, v223
	v_sub_f32_e32 v170, v155, v170
	v_cvt_pk_bf16_f32 v0, v170, 0
	v_and_b32_e32 v2, 0xffff, v0
	v_lshlrev_b32_e32 v0, 16, v0
	v_sub_f32_e32 v0, v170, v0
	v_cvt_pk_bf16_f32 v0, v0, 0
	v_lshl_or_b32 v0, v0, 16, v2
	v_mov_b32_e32 v2, v1
	v_mov_b32_e32 v3, v1
	v_add_u32_e32 v52, s10, v172
	ds_write_b128 v52, v[0:3] offset:128

.LBB0_802:
	s_waitcnt lgkmcnt(0)
	s_barrier
	v_add_f32_e32 v0, v84, v85
	s_add_i32 s10, s13, -3
	v_add_f32_e32 v175, v86, v0
	s_mov_b64 s[8:9], -1
	s_cmp_ge_i32 s10, s12
	s_mov_b64 s[10:11], -1
	s_cbranch_scc1 .LBB0_789
	s_cmp_ge_i32 s13, s12
	s_cbranch_scc1 .LBB0_807
	v_mov_b32_e32 v0, s19
	ds_read_b32 v0, v0 offset:16
	s_waitcnt lgkmcnt(0)
	v_lshlrev_b32_e32 v2, 6, v0
	v_add_u32_e32 v3, v2, v157
	v_mad_i64_i32 v[52:53], s[8:9], v3, s90, v[168:169]
	global_load_dwordx4 v[132:135], v[52:53], off offset:1024
	global_load_dwordx4 v[136:139], v[52:53], off offset:2048
	s_and_saveexec_b64 s[8:9], s[6:7]
	s_cbranch_execz .LBB0_806
	v_add_u32_e32 v2, v2, v159
	v_ashrrev_i32_e32 v3, 31, v2
	v_lshl_add_u64 v[2:3], v[2:3], 2, s[4:5]
	global_load_dword v170, v[2:3], off
	v_ashrrev_i32_e32 v0, 3, v0
	v_lshlrev_b32_e32 v0, 2, v0
	v_add_u32_e32 v0, s28, v0
	ds_read_b32 v223, v0

.LBB0_807:
	s_mulk_i32 s22, 0x4900
	v_add_u32_e32 v0, s22, v174
	ds_read_b128 v[52:55], v0
	ds_read_b128 v[56:59], v0 offset:32
	ds_read_b128 v[60:63], v0 offset:4608
	ds_read_b128 v[64:67], v0 offset:4640
	ds_read_b128 v[68:71], v0 offset:64
	ds_read_b128 v[72:75], v0 offset:96
	ds_read_b128 v[76:79], v0 offset:4672
	ds_read_b128 v[80:83], v0 offset:4704
	s_waitcnt lgkmcnt(7)
	v_mfma_f32_32x32x16_bf16 v[100:115], v[52:55], v[116:119], v[4:19]
	s_waitcnt lgkmcnt(5)
	v_mfma_f32_32x32x16_bf16 v[84:99], v[60:63], v[116:119], v[4:19]
	v_mfma_f32_32x32x16_bf16 v[100:115], v[56:59], v[120:123], v[100:115]
	ds_read_b128 v[52:55], v0 offset:128
	ds_read_b128 v[56:59], v0 offset:4736
	s_waitcnt lgkmcnt(6)
	v_mfma_f32_32x32x16_bf16 v[84:99], v[64:67], v[120:123], v[84:99]
	s_waitcnt lgkmcnt(5)
	v_mfma_f32_32x32x16_bf16 v[100:115], v[68:71], v[124:127], v[100:115]
	s_waitcnt lgkmcnt(3)
	v_mfma_f32_32x32x16_bf16 v[84:99], v[76:79], v[124:127], v[84:99]
	v_mfma_f32_32x32x16_bf16 v[100:115], v[72:75], v[128:131], v[100:115]
	s_waitcnt lgkmcnt(2)
	v_mfma_f32_32x32x16_bf16 v[84:99], v[80:83], v[128:131], v[84:99]
	s_waitcnt lgkmcnt(1)
	v_mfma_f32_32x32x16_bf16 v[100:115], v[52:55], v[148:151], v[100:115]
	s_waitcnt lgkmcnt(0)
	v_mfma_f32_32x32x16_bf16 v[84:99], v[56:59], v[148:151], v[84:99]
	v_mov_b32_e32 v2, s19
	ds_read_b32 v2, v2 offset:4
	s_waitcnt lgkmcnt(0)
	v_cmp_gt_i32_e32 vcc, s18, v2
	s_cbranch_vccnz .LBB0_809
	v_lshl_or_b32 v2, v2, 6, v158
	v_or_b32_e32 v3, 32, v2
	v_cmp_le_i32_e32 vcc, v2, v154
	v_or_b32_e32 v52, 34, v2
	s_nop 0
	v_cndmask_b32_e32 v100, v185, v100, vcc
	v_cmp_le_i32_e32 vcc, v3, v154
	v_or_b32_e32 v3, 33, v2
	s_nop 0
	v_cndmask_b32_e32 v84, v185, v84, vcc
	v_cmp_lt_i32_e32 vcc, v2, v154
	s_nop 1
	v_cndmask_b32_e32 v101, v185, v101, vcc
	v_cmp_le_i32_e32 vcc, v3, v154
	v_or_b32_e32 v3, 2, v2
	s_nop 0
	v_cndmask_b32_e32 v85, v185, v85, vcc
	v_cmp_le_i32_e32 vcc, v3, v154
	v_or_b32_e32 v3, 3, v2
	s_nop 0
	v_cndmask_b32_e32 v102, v185, v102, vcc
	v_cmp_le_i32_e32 vcc, v52, v154
	v_or_b32_e32 v52, 35, v2
	s_nop 0
	v_cndmask_b32_e32 v86, v185, v86, vcc
	v_cmp_le_i32_e32 vcc, v3, v154
	v_or_b32_e32 v3, 8, v2
	s_nop 0
	v_cndmask_b32_e32 v103, v185, v103, vcc
	v_cmp_le_i32_e32 vcc, v52, v154
	v_or_b32_e32 v52, 40, v2
	s_nop 0
	v_cndmask_b32_e32 v87, v185, v87, vcc
	v_cmp_le_i32_e32 vcc, v3, v154
	v_or_b32_e32 v3, 9, v2
	s_nop 0
	v_cndmask_b32_e32 v104, v185, v104, vcc
	v_cmp_le_i32_e32 vcc, v52, v154
	v_or_b32_e32 v52, 41, v2
	s_nop 0
	v_cndmask_b32_e32 v88, v185, v88, vcc
	v_cmp_le_i32_e32 vcc, v3, v154
	v_or_b32_e32 v3, 10, v2
	s_nop 0
	v_cndmask_b32_e32 v105, v185, v105, vcc
	v_cmp_le_i32_e32 vcc, v52, v154
	v_or_b32_e32 v52, 42, v2
	s_nop 0
	v_cndmask_b32_e32 v89, v185, v89, vcc
	v_cmp_le_i32_e32 vcc, v3, v154
	v_or_b32_e32 v3, 11, v2
	s_nop 0
	v_cndmask_b32_e32 v106, v185, v106, vcc
	v_cmp_le_i32_e32 vcc, v52, v154
	v_or_b32_e32 v52, 43, v2
	s_nop 0
	v_cndmask_b32_e32 v90, v185, v90, vcc
	v_cmp_le_i32_e32 vcc, v3, v154
	v_or_b32_e32 v3, 16, v2
	s_nop 0
	v_cndmask_b32_e32 v107, v185, v107, vcc
	v_cmp_le_i32_e32 vcc, v52, v154
	v_or_b32_e32 v52, 48, v2
	s_nop 0
	v_cndmask_b32_e32 v91, v185, v91, vcc
	v_cmp_le_i32_e32 vcc, v3, v154
	v_or_b32_e32 v3, 17, v2
	s_nop 0
	v_cndmask_b32_e32 v108, v185, v108, vcc
	v_cmp_le_i32_e32 vcc, v52, v154
	v_or_b32_e32 v52, 49, v2
	s_nop 0
	v_cndmask_b32_e32 v92, v185, v92, vcc
	v_cmp_le_i32_e32 vcc, v3, v154
	v_or_b32_e32 v3, 18, v2
	s_nop 0
	v_cndmask_b32_e32 v109, v185, v109, vcc
	v_cmp_le_i32_e32 vcc, v52, v154
	v_or_b32_e32 v52, 50, v2
	s_nop 0
	v_cndmask_b32_e32 v93, v185, v93, vcc
	v_cmp_le_i32_e32 vcc, v3, v154
	v_or_b32_e32 v3, 19, v2
	s_nop 0
	v_cndmask_b32_e32 v110, v185, v110, vcc
	v_cmp_le_i32_e32 vcc, v52, v154
	v_or_b32_e32 v52, 51, v2
	s_nop 0
	v_cndmask_b32_e32 v94, v185, v94, vcc
	v_cmp_le_i32_e32 vcc, v3, v154
	v_or_b32_e32 v3, 24, v2
	s_nop 0
	v_cndmask_b32_e32 v111, v185, v111, vcc
	v_cmp_le_i32_e32 vcc, v52, v154
	v_or_b32_e32 v52, 56, v2
	s_nop 0
	v_cndmask_b32_e32 v95, v185, v95, vcc
	v_cmp_le_i32_e32 vcc, v3, v154
	v_or_b32_e32 v3, 25, v2
	s_nop 0
	v_cndmask_b32_e32 v112, v185, v112, vcc
	v_cmp_le_i32_e32 vcc, v52, v154
	v_or_b32_e32 v52, 57, v2
	s_nop 0
	v_cndmask_b32_e32 v96, v185, v96, vcc
	v_cmp_le_i32_e32 vcc, v3, v154
	v_or_b32_e32 v3, 26, v2
	s_nop 0
	v_cndmask_b32_e32 v113, v185, v113, vcc
	v_cmp_le_i32_e32 vcc, v52, v154
	v_or_b32_e32 v52, 58, v2
	s_nop 0
	v_cndmask_b32_e32 v97, v185, v97, vcc
	v_cmp_le_i32_e32 vcc, v3, v154
	v_or_b32_e32 v3, 27, v2
	v_or_b32_e32 v2, 59, v2
	v_cndmask_b32_e32 v114, v185, v114, vcc
	v_cmp_le_i32_e32 vcc, v52, v154
	s_nop 1
	v_cndmask_b32_e32 v98, v185, v98, vcc
	v_cmp_le_i32_e32 vcc, v3, v154
	s_nop 1
	v_cndmask_b32_e32 v115, v185, v115, vcc
	v_cmp_le_i32_e32 vcc, v2, v154
	s_nop 1
	v_cndmask_b32_e32 v99, v185, v99, vcc
.LBB0_809:
	s_nop 4
	v_max3_f32 v2, v100, v101, v102
	s_nop 0
	v_max3_f32 v3, v84, v85, v86
	v_max3_f32 v2, v2, v103, v104
	v_max3_f32 v3, v3, v87, v88
	v_max3_f32 v2, v2, v105, v106
	v_max3_f32 v3, v3, v89, v90
	v_max3_f32 v2, v2, v107, v108
	v_max3_f32 v3, v3, v91, v92
	v_max3_f32 v2, v2, v109, v110
	v_max3_f32 v3, v3, v93, v94
	v_max3_f32 v2, v2, v111, v112
	v_max3_f32 v3, v3, v95, v96
	v_max_f32_e32 v52, v99, v99
	v_max_f32_e32 v53, v115, v115
	v_max3_f32 v2, v2, v113, v114
	v_max3_f32 v3, v3, v97, v98
	v_max_f32_e32 v52, v53, v52
	v_max3_f32 v2, v2, v3, v52
	v_mov_b32_e32 v3, v2
	s_nop 1
	v_permlane32_swap_b32_e32 v2, v3
	v_max_f32_e32 v3, v3, v3
	v_max_f32_e32 v2, v2, v2
	v_max_f32_e32 v2, v2, v3
	v_cmp_lt_f32_e32 vcc, s91, v2
	s_cbranch_vccz .LBB0_811
	v_max_f32_e32 v2, v2, v2
	v_max_f32_e32 v2, 0, v2
	v_exp_f32_e64 v52, -v2
	v_pk_add_f32 v[100:101], v[100:101], v[2:3] op_sel_hi:[1,0] neg_lo:[0,1] neg_hi:[0,1]
	v_pk_add_f32 v[84:85], v[84:85], v[2:3] op_sel_hi:[1,0] neg_lo:[0,1] neg_hi:[0,1]
	v_pk_add_f32 v[102:103], v[102:103], v[2:3] op_sel_hi:[1,0] neg_lo:[0,1] neg_hi:[0,1]
	v_mul_f32_e32 v176, v175, v52
	v_pk_add_f32 v[86:87], v[86:87], v[2:3] op_sel_hi:[1,0] neg_lo:[0,1] neg_hi:[0,1]
	v_pk_add_f32 v[104:105], v[104:105], v[2:3] op_sel_hi:[1,0] neg_lo:[0,1] neg_hi:[0,1]
	v_pk_add_f32 v[88:89], v[88:89], v[2:3] op_sel_hi:[1,0] neg_lo:[0,1] neg_hi:[0,1]
	v_pk_add_f32 v[106:107], v[106:107], v[2:3] op_sel_hi:[1,0] neg_lo:[0,1] neg_hi:[0,1]
	v_pk_add_f32 v[90:91], v[90:91], v[2:3] op_sel_hi:[1,0] neg_lo:[0,1] neg_hi:[0,1]
	v_pk_add_f32 v[108:109], v[108:109], v[2:3] op_sel_hi:[1,0] neg_lo:[0,1] neg_hi:[0,1]
	v_pk_add_f32 v[92:93], v[92:93], v[2:3] op_sel_hi:[1,0] neg_lo:[0,1] neg_hi:[0,1]
	v_pk_add_f32 v[110:111], v[110:111], v[2:3] op_sel_hi:[1,0] neg_lo:[0,1] neg_hi:[0,1]
	v_pk_add_f32 v[94:95], v[94:95], v[2:3] op_sel_hi:[1,0] neg_lo:[0,1] neg_hi:[0,1]
	v_pk_add_f32 v[112:113], v[112:113], v[2:3] op_sel_hi:[1,0] neg_lo:[0,1] neg_hi:[0,1]
	v_pk_add_f32 v[96:97], v[96:97], v[2:3] op_sel_hi:[1,0] neg_lo:[0,1] neg_hi:[0,1]
	v_pk_add_f32 v[114:115], v[114:115], v[2:3] op_sel_hi:[1,0] neg_lo:[0,1] neg_hi:[0,1]
	v_pk_add_f32 v[98:99], v[98:99], v[2:3] op_sel_hi:[1,0] neg_lo:[0,1] neg_hi:[0,1]
	v_sub_f32_e32 v19, v19, v2
	v_sub_f32_e32 v18, v18, v2
	v_sub_f32_e32 v17, v17, v2
	v_sub_f32_e32 v16, v16, v2
	v_sub_f32_e32 v15, v15, v2
	v_sub_f32_e32 v14, v14, v2
	v_sub_f32_e32 v13, v13, v2
	v_sub_f32_e32 v12, v12, v2
	v_sub_f32_e32 v11, v11, v2
	v_sub_f32_e32 v10, v10, v2
	v_sub_f32_e32 v9, v9, v2
	v_sub_f32_e32 v8, v8, v2
	v_sub_f32_e32 v7, v7, v2
	v_sub_f32_e32 v6, v6, v2
	v_sub_f32_e32 v5, v5, v2
	v_sub_f32_e32 v4, v4, v2
	v_pk_mul_f32 v[50:51], v[50:51], v[52:53] op_sel_hi:[1,0]
	v_pk_mul_f32 v[48:49], v[48:49], v[52:53] op_sel_hi:[1,0]
	v_pk_mul_f32 v[46:47], v[46:47], v[52:53] op_sel_hi:[1,0]
	v_pk_mul_f32 v[44:45], v[44:45], v[52:53] op_sel_hi:[1,0]
	v_pk_mul_f32 v[42:43], v[42:43], v[52:53] op_sel_hi:[1,0]
	v_pk_mul_f32 v[40:41], v[40:41], v[52:53] op_sel_hi:[1,0]
	v_pk_mul_f32 v[38:39], v[38:39], v[52:53] op_sel_hi:[1,0]
	v_pk_mul_f32 v[36:37], v[36:37], v[52:53] op_sel_hi:[1,0]
	v_pk_mul_f32 v[34:35], v[34:35], v[52:53] op_sel_hi:[1,0]
	v_pk_mul_f32 v[32:33], v[32:33], v[52:53] op_sel_hi:[1,0]
	v_pk_mul_f32 v[30:31], v[30:31], v[52:53] op_sel_hi:[1,0]
	v_pk_mul_f32 v[28:29], v[28:29], v[52:53] op_sel_hi:[1,0]
	v_pk_mul_f32 v[26:27], v[26:27], v[52:53] op_sel_hi:[1,0]
	v_pk_mul_f32 v[24:25], v[24:25], v[52:53] op_sel_hi:[1,0]
	v_pk_mul_f32 v[22:23], v[22:23], v[52:53] op_sel_hi:[1,0]
	v_pk_mul_f32 v[20:21], v[20:21], v[52:53] op_sel_hi:[1,0]
	s_branch .LBB0_812
.LBB0_811:
	v_mov_b32_e32 v176, v175

.LBB0_817:
.LBB0_818:
	v_mov_b32_e32 v86, v175
